# K and partner-P fragment LDS reads issued at the head of the step, before the partner-max exchange logic (counted lgkmcnt)
# speedup vs baseline: 1.0479x; 1.0004x over previous
; template <int KB> __device__ __forceinline__ void qkt_half(f32x16& p, const char* K_lds, int r32, int hi, int kh, const char* qf, bf16x8 q0) {
;     p = f32x16{};
;     const char* kb[4];
; #pragma unroll
;     for (int dd = 0; dd < 4; ++dd) kb[dd] = K_lds + KB * SHM_K + kh * 8192 + KSWZ(r32, (dd * 16 + hi * 8) * 2);
; #pragma unroll
;     for (int d0 = 0; d0 < 8; ++d0) { const bf16x8 b0 = *reinterpret_cast<const bf16x8*>(kb[d0 & 3] + (d0 >> 2) * 128); const bf16x8 q = d0 == 0 ? q0 : *reinterpret_cast<const bf16x8*>(qf + (d0 - 1) * 1024); p = __builtin_amdgcn_mfma_f32_32x32x16_bf16(b0, q, p, 0, 0, 0); }
; }
.LBB0_368:
	ds_read_b32 v65, v197 offset:1024
	ds_read_b128 v[184:187], v220 offset:16384
	ds_read_b128 v[180:183], v220 offset:17408
	ds_read_b128 v[96:99], v211
	ds_read_b128 v[68:71], v212
	ds_read_b128 v[72:75], v213
	ds_read_b128 v[76:79], v214
	ds_read_b128 v[80:83], v211 offset:128
	ds_read_b128 v[84:87], v212 offset:128
	ds_read_b128 v[88:91], v213 offset:128
	ds_read_b128 v[92:95], v214 offset:128
	v_max_f32_e32 v64, v64, v64
	v_mov_b32_e32 v229, 1.0
	s_waitcnt lgkmcnt(10)
	v_max_f32_e32 v65, v65, v65
	v_max_f32_e32 v64, v64, v65
	v_sub_f32_e32 v65, v64, v218
	v_mul_f32_e32 v65, 0x3db504f3, v65
	v_cmp_ge_f32_e32 vcc, s72, v65
	s_cmp_eq_u64 vcc, exec
	s_cbranch_scc0 .LBB0_402
.LBB0_369:
	s_waitcnt lgkmcnt(7)
	v_mfma_f32_32x32x16_bf16 v[128:143], v[96:99], v[144:147], 0
	s_waitcnt lgkmcnt(6)
	v_mfma_f32_32x32x16_bf16 v[128:143], v[68:71], v[148:151], v[128:143]
	s_add_i32 s90, s87, -3
	s_cmp_gt_u32 s90, s84
	s_cbranch_scc1 .Ld0_h1_noK
	s_add_i32 s90, s87, -2
	s_cmp_lg_u64 s[46:47], 0
	s_cselect_b32 s90, s90, s53
	s_lshl_b32 s90, s90, 14
	s_add_u32 s92, s98, s90
	s_addc_u32 s93, s99, 0
	s_add_i32 m0, s100, 0x14000
	s_nop 0
	global_load_lds_dwordx4 v250, s[92:93]
	s_add_u32 s92, s92, 0x2000
	s_addc_u32 s93, s93, 0
	s_add_i32 m0, s100, 0x16000
	s_nop 0
	global_load_lds_dwordx4 v250, s[92:93]

; template <int KB> __device__ __forceinline__ void qkt_half(f32x16& p, const char* K_lds, int r32, int hi, int kh, const char* qf, bf16x8 q0) {
;     p = f32x16{};
;     const char* kb[4];
; #pragma unroll
;     for (int dd = 0; dd < 4; ++dd) kb[dd] = K_lds + KB * SHM_K + kh * 8192 + KSWZ(r32, (dd * 16 + hi * 8) * 2);
; #pragma unroll
;     for (int d0 = 0; d0 < 8; ++d0) { const bf16x8 b0 = *reinterpret_cast<const bf16x8*>(kb[d0 & 3] + (d0 >> 2) * 128); const bf16x8 q = d0 == 0 ? q0 : *reinterpret_cast<const bf16x8*>(qf + (d0 - 1) * 1024); p = __builtin_amdgcn_mfma_f32_32x32x16_bf16(b0, q, p, 0, 0, 0); }
; }
.LBB0_377:
	s_waitcnt vmcnt(0) lgkmcnt(0)
	s_barrier
	ds_read_b32 v1, v197
	ds_read_b128 v[184:187], v220
	ds_read_b128 v[180:183], v220 offset:1024
	ds_read_b128 v[32:35], v222
	ds_read_b128 v[4:7], v223
	ds_read_b128 v[8:11], v224
	ds_read_b128 v[12:15], v225
	ds_read_b128 v[16:19], v222 offset:128
	ds_read_b128 v[20:23], v223 offset:128
	ds_read_b128 v[24:27], v224 offset:128
	ds_read_b128 v[28:31], v225 offset:128
	v_max_f32_e32 v0, v0, v0
	v_mov_b32_e32 v230, 1.0
	s_waitcnt lgkmcnt(10)
	v_max_f32_e32 v1, v1, v1
	v_max_f32_e32 v0, v0, v1
	v_sub_f32_e32 v1, v0, v218
	v_mul_f32_e32 v1, 0x3db504f3, v1
	v_cmp_ge_f32_e32 vcc, s72, v1
	s_cmp_eq_u64 vcc, exec
	s_cbranch_scc0 .LBB0_403
.LBB0_386:
	s_waitcnt lgkmcnt(7)
	v_mfma_f32_32x32x16_bf16 v[128:143], v[32:35], v[144:147], 0
	s_waitcnt lgkmcnt(6)
	v_mfma_f32_32x32x16_bf16 v[128:143], v[4:7], v[148:151], v[128:143]
	s_add_i32 s90, s87, -1
	s_cmp_gt_u32 s90, s85
	s_cbranch_scc1 .Ld0_h2_noK
	s_add_i32 s91, s53, -1
	s_cmp_lg_u64 s[46:47], 0
	s_cselect_b32 s90, s90, s91
	s_lshl_b32 s90, s90, 14
	s_add_u32 s92, s98, s90
	s_addc_u32 s93, s99, 0
	s_add_i32 m0, s100, 0x10000
	s_nop 0
	global_load_lds_dwordx4 v250, s[92:93]
	s_add_u32 s92, s92, 0x2000
	s_addc_u32 s93, s93, 0
	s_add_i32 m0, s100, 0x12000
	s_nop 0
	global_load_lds_dwordx4 v250, s[92:93]
